# sample-token attention units remapped so the 8 new tokens of a sequence run on workgroups of one XCD (shared L2 for the compressed and window keys)
# speedup vs baseline: 1.0350x; 1.0072x over previous
.LBB0_716:
	s_and_b32 s100, s67, 7
	s_lshl_b32 s100, s100, 2
	s_lshr_b32 s101, s67, 6
	s_add_i32 s100, s100, s101
	s_lshl_b32 s100, s100, 3
	s_bfe_u32 s101, s67, 0x30003
	s_or_b32 s101, s100, s101
	s_and_b32 s68, s101, 7
	s_and_b32 s69, s101, -8
	s_or_b32 s2, s69, s68
	s_add_i32 s58, s2, 0x4000
	s_ashr_i32 s59, s58, 31
	v_mov_b32_e32 v133, v134
	s_lshl_b64 s[2:3], s[58:59], 9
	s_add_u32 s2, s28, s2
	v_ashrrev_i32_e32 v97, 5, v133
	s_waitcnt vmcnt(0)
	v_and_b32_e32 v83, 3, v133
	s_addc_u32 s3, s30, s3
	v_lshlrev_b32_e32 v0, 7, v83
	v_mov_b32_e32 v1, v96
	v_lshlrev_b32_e32 v2, 3, v97
	v_lshl_add_u64 v[0:1], s[2:3], 0, v[0:1]
	v_ashrrev_i32_e32 v3, 31, v2
	v_lshl_add_u64 v[0:1], v[2:3], 1, v[0:1]
	s_mul_i32 s2, s58, 0x2800
	global_load_dwordx4 v[48:51], v[0:1], off
	global_load_dwordx4 v[52:55], v[0:1], off offset:32
	global_load_dwordx4 v[56:59], v[0:1], off offset:64
	global_load_dwordx4 v[60:63], v[0:1], off offset:96
	s_mul_hi_i32 s3, s58, 0x2800
	s_add_u32 s2, s14, s2
	v_mul_u32_u24_e32 v0, 3, v83
	s_addc_u32 s3, s15, s3
	v_lshlrev_b32_e32 v0, 2, v0
	v_mov_b32_e32 v1, v96
	v_lshl_add_u64 v[0:1], s[2:3], 0, v[0:1]
	s_mov_b32 s2, 0xdea2000
	v_add_co_u32_e32 v0, vcc, s2, v0
	v_add_u32_e32 v104, s90, v133
	s_nop 0
	v_addc_co_u32_e32 v1, vcc, 0, v1, vcc
	global_load_dwordx3 v[80:82], v[0:1], off offset:2080
	v_cmp_gt_i32_e32 vcc, 64, v104
	v_lshl_add_u32 v105, v104, 2, 0
	s_waitcnt vmcnt(0)
	s_barrier
	v_cmp_nlt_f32_e64 s[54:55], s34, v80
	v_cmp_ngt_f32_e64 s[56:57], s35, v80
	v_cmp_nlt_f32_e64 s[50:51], s34, v81
	v_cmp_ngt_f32_e64 s[46:47], s35, v81
	v_cmp_nlt_f32_e64 s[52:53], s34, v82
	v_cmp_ngt_f32_e64 s[48:49], s35, v82
	s_and_saveexec_b64 s[4:5], vcc
	v_add_u32_e32 v0, 0x13000, v105
	ds_write_b32 v0, v96
	s_or_b64 exec, exec, s[4:5]
	v_mov_b32_e32 v2, v133
	v_readlane_b32 s2, v254, 40
	v_ashrrev_i32_e32 v0, 1, v2
	s_ashr_i32 s62, s101, 3
	v_add_u32_e32 v0, s2, v0
	s_movk_i32 s2, 0x1ff
	v_cmp_gt_i32_e32 vcc, s2, v0
	s_ashr_i32 s63, s62, 31
	s_add_u32 s6, s16, s62
	v_cndmask_b32_e32 v0, 0, v0, vcc
	s_addc_u32 s7, s17, s63
	v_ashrrev_i32_e32 v1, 31, v0
	v_mov_b32_e32 v3, 0x1ff
	s_mulk_i32 s7, 0x1ff
	v_mad_u64_u32 v[0:1], s[2:3], s6, v3, v[0:1]
	v_add_u32_e32 v1, s7, v1
	v_lshlrev_b64 v[0:1], 8, v[0:1]
	v_lshlrev_b32_e32 v2, 7, v2
	v_lshl_add_u64 v[0:1], s[22:23], 0, v[0:1]
	v_and_b32_e32 v2, 0x80, v2
	v_mov_b32_e32 v3, v96
	v_lshl_add_u64 v[16:17], v[0:1], 0, v[2:3]
	v_mov_b32_e32 v0, 0
	v_mov_b32_e32 v4, 0
	v_mov_b32_e32 v5, 0
	v_mov_b32_e32 v6, 0
	v_mov_b32_e32 v7, 0
	v_mov_b32_e32 v8, 0
	v_mov_b32_e32 v9, 0
	v_mov_b32_e32 v10, 0
	v_mov_b32_e32 v11, 0
	s_and_saveexec_b64 s[4:5], vcc
	s_cbranch_execz .LBB0_720
	global_load_dwordx4 v[4:7], v[16:17], off
	global_load_dwordx4 v[8:11], v[16:17], off offset:16

	.amdhsa_kernel _Z9hymba_fwd6Params
		.amdhsa_group_segment_fixed_size 0
		.amdhsa_private_segment_fixed_size 0
		.amdhsa_kernarg_size 552
		.amdhsa_user_sgpr_count 2
		.amdhsa_user_sgpr_dispatch_ptr 0
		.amdhsa_user_sgpr_queue_ptr 0
		.amdhsa_user_sgpr_kernarg_segment_ptr 1
		.amdhsa_user_sgpr_dispatch_id 0
		.amdhsa_user_sgpr_kernarg_preload_length 0
		.amdhsa_user_sgpr_kernarg_preload_offset 0
		.amdhsa_user_sgpr_private_segment_size 0
		.amdhsa_uses_dynamic_stack 0
		.amdhsa_enable_private_segment 0
		.amdhsa_system_sgpr_workgroup_id_x 1
		.amdhsa_system_sgpr_workgroup_id_y 0
		.amdhsa_system_sgpr_workgroup_id_z 0
		.amdhsa_system_sgpr_workgroup_info 0
		.amdhsa_system_vgpr_workitem_id 0
		.amdhsa_next_free_vgpr 256
		.amdhsa_next_free_sgpr 102
		.amdhsa_accum_offset 256
		.amdhsa_reserve_vcc 1
		.amdhsa_float_round_mode_32 0
		.amdhsa_float_round_mode_16_64 0
		.amdhsa_float_denorm_mode_32 3
		.amdhsa_float_denorm_mode_16_64 3
		.amdhsa_dx10_clamp 1
		.amdhsa_ieee_mode 1
		.amdhsa_fp16_overflow 0
		.amdhsa_tg_split 0
		.amdhsa_exception_fp_ieee_invalid_op 0
		.amdhsa_exception_fp_denorm_src 0
		.amdhsa_exception_fp_ieee_div_zero 0
		.amdhsa_exception_fp_ieee_overflow 0
		.amdhsa_exception_fp_ieee_underflow 0
		.amdhsa_exception_fp_ieee_inexact 0
		.amdhsa_exception_int_div_zero 0
	.end_amdhsa_kernel

amdhsa.kernels:
  - .agpr_count:     0
    .args:
      - .offset:         0
        .size:           296
        .value_kind:     by_value
      - .offset:         296
        .size:           4
        .value_kind:     hidden_block_count_x
      - .offset:         300
        .size:           4
        .value_kind:     hidden_block_count_y
      - .offset:         304
        .size:           4
        .value_kind:     hidden_block_count_z
      - .offset:         308
        .size:           2
        .value_kind:     hidden_group_size_x
      - .offset:         310
        .size:           2
        .value_kind:     hidden_group_size_y
      - .offset:         312
        .size:           2
        .value_kind:     hidden_group_size_z
      - .offset:         314
        .size:           2
        .value_kind:     hidden_remainder_x
      - .offset:         316
        .size:           2
        .value_kind:     hidden_remainder_y
      - .offset:         318
        .size:           2
        .value_kind:     hidden_remainder_z
      - .offset:         336
        .size:           8
        .value_kind:     hidden_global_offset_x
      - .offset:         344
        .size:           8
        .value_kind:     hidden_global_offset_y
      - .offset:         352
        .size:           8
        .value_kind:     hidden_global_offset_z
      - .offset:         360
        .size:           2
        .value_kind:     hidden_grid_dims
      - .offset:         416
        .size:           4
        .value_kind:     hidden_dynamic_lds_size
    .group_segment_fixed_size: 0
    .kernarg_segment_align: 8
    .kernarg_segment_size: 552
    .language:       OpenCL C
    .language_version:
      - 2
      - 0
    .max_flat_workgroup_size: 512
    .name:           _Z9hymba_fwd6Params
    .private_segment_fixed_size: 0
    .sgpr_count:     108
    .sgpr_spill_count: 267
    .symbol:         _Z9hymba_fwd6Params.kd
    .uniform_work_group_size: 1
    .uses_dynamic_stack: false
    .vgpr_count:     256
    .vgpr_spill_count: 0
    .wavefront_size: 64
